# branch-merge GEMM: mid-K gate rescale hook pipelined (16 gate loads in flight per batch, counted vmcnt) instead of 16 serialized load->vmcnt(0)->rescale steps
# speedup vs baseline: 1.0182x; 1.0180x over previous
; __device__ __forceinline__ float bflo(unsigned w) { return __uint_as_float(w << 16); }
; __device__ __forceinline__ float bfhi(unsigned w) { return __uint_as_float(w & 0xffff0000u); }
;     __device__ __forceinline__ void mid(f32x4 (&acc)[2][2][4][2], const pg8::Unit& u, int seg, int wr, int wc, int fr, int fq) const {
;         asm volatile("" : "+v"(fr), "+v"(fq));
;         const int row0 = u.pm * 256 + wr * 64 + fr, col0 = u.pn * 256 + wc * 32 + 8 * fq;
; #pragma unroll
;         for (int ai = 0; ai < 2; ++ai)
; #pragma unroll
;             for (int m = 0; m < 4; ++m) {
;                 const bf16_t* gp = gates + (size_t)(row0 + ai * 128 + m * 16) * 3072 + seg * 1024 + col0;
; #pragma unroll
;                 for (int bj = 0; bj < 2; ++bj) {
;                     const u32x4 gw = *(const u32x4*)(gp + bj * 128), hw = *(const u32x4*)(gp + 1024 + bj * 128);
;                     f32x4 v0 = acc[ai][bj][m][0], v1 = acc[ai][bj][m][1];
;                     v0[0] *= bflo(gw.x) * __builtin_amdgcn_rcpf(fmaxf(bflo(hw.x), 1e-20f)); v0[1] *= bfhi(gw.x) * __builtin_amdgcn_rcpf(fmaxf(bfhi(hw.x), 1e-20f));
;                     v0[2] *= bflo(gw.y) * __builtin_amdgcn_rcpf(fmaxf(bflo(hw.y), 1e-20f)); v0[3] *= bfhi(gw.y) * __builtin_amdgcn_rcpf(fmaxf(bfhi(hw.y), 1e-20f));
;                     v1[0] *= bflo(gw.z) * __builtin_amdgcn_rcpf(fmaxf(bflo(hw.z), 1e-20f)); v1[1] *= bfhi(gw.z) * __builtin_amdgcn_rcpf(fmaxf(bfhi(hw.z), 1e-20f));
;                     v1[2] *= bflo(gw.w) * __builtin_amdgcn_rcpf(fmaxf(bflo(hw.w), 1e-20f)); v1[3] *= bfhi(gw.w) * __builtin_amdgcn_rcpf(fmaxf(bfhi(hw.w), 1e-20f));
;                     acc[ai][bj][m][0] = v0; acc[ai][bj][m][1] = v1;
;                 }
;                 if (m & 1) asm volatile("" ::: "memory");
;             }
.LBB0_111:
	s_cmpk_eq_i32 s56, 0x400
	s_cselect_b32 s28, 0, 0x800
	v_add_u32_e32 v162, s89, v164
	v_lshl_add_u32 v163, v165, 3, s88
	v_mul_u32_u24_e32 v162, 0x1800, v162
	v_lshl_add_u32 v162, v163, 1, v162
	v_add_u32_e32 v162, s28, v162
	global_load_dwordx4 v[198:201], v162, s[12:13]
	global_load_dwordx4 v[202:205], v162, s[12:13] offset:2048
	global_load_dwordx4 v[206:209], v162, s[12:13] offset:256
	global_load_dwordx4 v[210:213], v162, s[12:13] offset:2304
	v_add_u32_e32 v163, 0x18000, v162
	global_load_dwordx4 v[214:217], v163, s[12:13]
	global_load_dwordx4 v[218:221], v163, s[12:13] offset:2048
	global_load_dwordx4 v[222:225], v163, s[12:13] offset:256
	global_load_dwordx4 v[226:229], v163, s[12:13] offset:2304
	v_add_u32_e32 v163, 0x30000, v162
	global_load_dwordx4 v[230:233], v163, s[12:13]
	global_load_dwordx4 v[234:237], v163, s[12:13] offset:2048
	global_load_dwordx4 v[238:241], v163, s[12:13] offset:256
	global_load_dwordx4 v[130:133], v163, s[12:13] offset:2304
	v_add_u32_e32 v163, 0x48000, v162
	global_load_dwordx4 v[134:137], v163, s[12:13]
	global_load_dwordx4 v[170:173], v163, s[12:13] offset:2048
	global_load_dwordx4 v[174:177], v163, s[12:13] offset:256
	global_load_dwordx4 v[178:181], v163, s[12:13] offset:2304
	s_waitcnt vmcnt(14)
	v_lshlrev_b32_e32 v246, 16, v202
	v_and_b32_e32 v247, 0xffff0000, v202
	v_max_f32_e32 v246, 0x1e3ce508, v246
	v_max_f32_e32 v247, 0x1e3ce508, v247
	v_rcp_f32_e32 v246, v246
	v_rcp_f32_e32 v247, v247
	v_lshlrev_b32_e32 v248, 16, v198
	v_and_b32_e32 v249, 0xffff0000, v198
	v_pk_mul_f32 v[248:249], v[246:247], v[248:249]
	v_pk_mul_f32 v[126:127], v[126:127], v[248:249]
	v_lshlrev_b32_e32 v250, 16, v203
	v_and_b32_e32 v251, 0xffff0000, v203
	v_max_f32_e32 v250, 0x1e3ce508, v250
	v_max_f32_e32 v251, 0x1e3ce508, v251
	v_rcp_f32_e32 v250, v250
	v_rcp_f32_e32 v251, v251
	v_lshlrev_b32_e32 v252, 16, v199
	v_and_b32_e32 v253, 0xffff0000, v199
	v_pk_mul_f32 v[252:253], v[250:251], v[252:253]
	v_pk_mul_f32 v[128:129], v[128:129], v[252:253]
	v_lshlrev_b32_e32 v246, 16, v204
	v_and_b32_e32 v247, 0xffff0000, v204
	v_max_f32_e32 v246, 0x1e3ce508, v246
	v_max_f32_e32 v247, 0x1e3ce508, v247
	v_rcp_f32_e32 v246, v246
	v_rcp_f32_e32 v247, v247
	v_lshlrev_b32_e32 v248, 16, v200
	v_and_b32_e32 v249, 0xffff0000, v200
	v_pk_mul_f32 v[248:249], v[246:247], v[248:249]
	v_pk_mul_f32 v[122:123], v[122:123], v[248:249]
	v_lshlrev_b32_e32 v250, 16, v205
	v_and_b32_e32 v251, 0xffff0000, v205
	v_max_f32_e32 v250, 0x1e3ce508, v250
	v_max_f32_e32 v251, 0x1e3ce508, v251
	v_rcp_f32_e32 v250, v250
	v_rcp_f32_e32 v251, v251
	v_lshlrev_b32_e32 v252, 16, v201
	v_and_b32_e32 v253, 0xffff0000, v201
	v_pk_mul_f32 v[252:253], v[250:251], v[252:253]
	v_pk_mul_f32 v[124:125], v[124:125], v[252:253]
	s_waitcnt vmcnt(12)
	v_lshlrev_b32_e32 v246, 16, v210
	v_and_b32_e32 v247, 0xffff0000, v210
	v_max_f32_e32 v246, 0x1e3ce508, v246
	v_max_f32_e32 v247, 0x1e3ce508, v247
	v_rcp_f32_e32 v246, v246
	v_rcp_f32_e32 v247, v247
	v_lshlrev_b32_e32 v248, 16, v206
	v_and_b32_e32 v249, 0xffff0000, v206
	v_pk_mul_f32 v[248:249], v[246:247], v[248:249]
	v_pk_mul_f32 v[118:119], v[118:119], v[248:249]
	v_lshlrev_b32_e32 v250, 16, v211
	v_and_b32_e32 v251, 0xffff0000, v211
	v_max_f32_e32 v250, 0x1e3ce508, v250
	v_max_f32_e32 v251, 0x1e3ce508, v251
	v_rcp_f32_e32 v250, v250
	v_rcp_f32_e32 v251, v251
	v_lshlrev_b32_e32 v252, 16, v207
	v_and_b32_e32 v253, 0xffff0000, v207
	v_pk_mul_f32 v[252:253], v[250:251], v[252:253]
	v_pk_mul_f32 v[120:121], v[120:121], v[252:253]
	v_lshlrev_b32_e32 v246, 16, v212
	v_and_b32_e32 v247, 0xffff0000, v212
	v_max_f32_e32 v246, 0x1e3ce508, v246
	v_max_f32_e32 v247, 0x1e3ce508, v247
	v_rcp_f32_e32 v246, v246
	v_rcp_f32_e32 v247, v247
	v_lshlrev_b32_e32 v248, 16, v208
	v_and_b32_e32 v249, 0xffff0000, v208
	v_pk_mul_f32 v[248:249], v[246:247], v[248:249]
	v_pk_mul_f32 v[114:115], v[114:115], v[248:249]
	v_lshlrev_b32_e32 v250, 16, v213
	v_and_b32_e32 v251, 0xffff0000, v213
	v_max_f32_e32 v250, 0x1e3ce508, v250
	v_max_f32_e32 v251, 0x1e3ce508, v251
	v_rcp_f32_e32 v250, v250
	v_rcp_f32_e32 v251, v251
	v_lshlrev_b32_e32 v252, 16, v209
	v_and_b32_e32 v253, 0xffff0000, v209
	v_pk_mul_f32 v[252:253], v[250:251], v[252:253]
	v_pk_mul_f32 v[116:117], v[116:117], v[252:253]
	s_waitcnt vmcnt(10)
	v_lshlrev_b32_e32 v246, 16, v218
	v_and_b32_e32 v247, 0xffff0000, v218
	v_max_f32_e32 v246, 0x1e3ce508, v246
	v_max_f32_e32 v247, 0x1e3ce508, v247
	v_rcp_f32_e32 v246, v246
	v_rcp_f32_e32 v247, v247
	v_lshlrev_b32_e32 v248, 16, v214
	v_and_b32_e32 v249, 0xffff0000, v214
	v_pk_mul_f32 v[248:249], v[246:247], v[248:249]
	v_pk_mul_f32 v[110:111], v[110:111], v[248:249]
	v_lshlrev_b32_e32 v250, 16, v219
	v_and_b32_e32 v251, 0xffff0000, v219
	v_max_f32_e32 v250, 0x1e3ce508, v250
	v_max_f32_e32 v251, 0x1e3ce508, v251
	v_rcp_f32_e32 v250, v250
	v_rcp_f32_e32 v251, v251
	v_lshlrev_b32_e32 v252, 16, v215
	v_and_b32_e32 v253, 0xffff0000, v215
	v_pk_mul_f32 v[252:253], v[250:251], v[252:253]
	v_pk_mul_f32 v[112:113], v[112:113], v[252:253]
	v_lshlrev_b32_e32 v246, 16, v220
	v_and_b32_e32 v247, 0xffff0000, v220
	v_max_f32_e32 v246, 0x1e3ce508, v246
	v_max_f32_e32 v247, 0x1e3ce508, v247
	v_rcp_f32_e32 v246, v246
	v_rcp_f32_e32 v247, v247
	v_lshlrev_b32_e32 v248, 16, v216
	v_and_b32_e32 v249, 0xffff0000, v216
	v_pk_mul_f32 v[248:249], v[246:247], v[248:249]
	v_pk_mul_f32 v[106:107], v[106:107], v[248:249]
	v_lshlrev_b32_e32 v250, 16, v221
	v_and_b32_e32 v251, 0xffff0000, v221
	v_max_f32_e32 v250, 0x1e3ce508, v250
	v_max_f32_e32 v251, 0x1e3ce508, v251
	v_rcp_f32_e32 v250, v250
	v_rcp_f32_e32 v251, v251
	v_lshlrev_b32_e32 v252, 16, v217
	v_and_b32_e32 v253, 0xffff0000, v217
	v_pk_mul_f32 v[252:253], v[250:251], v[252:253]
	v_pk_mul_f32 v[108:109], v[108:109], v[252:253]
	s_waitcnt vmcnt(8)
; __device__ __forceinline__ float bflo(unsigned w) { return __uint_as_float(w << 16); }
; __device__ __forceinline__ float bfhi(unsigned w) { return __uint_as_float(w & 0xffff0000u); }
;     __device__ __forceinline__ void mid(f32x4 (&acc)[2][2][4][2], const pg8::Unit& u, int seg, int wr, int wc, int fr, int fq) const {
;     ...
;                 const bf16_t* gp = gates + (size_t)(row0 + ai * 128 + m * 16) * 3072 + seg * 1024 + col0;
; #pragma unroll
;                 for (int bj = 0; bj < 2; ++bj) {
;                     const u32x4 gw = *(const u32x4*)(gp + bj * 128), hw = *(const u32x4*)(gp + 1024 + bj * 128);
;                     f32x4 v0 = acc[ai][bj][m][0], v1 = acc[ai][bj][m][1];
;                     v0[0] *= bflo(gw.x) * __builtin_amdgcn_rcpf(fmaxf(bflo(hw.x), 1e-20f)); v0[1] *= bfhi(gw.x) * __builtin_amdgcn_rcpf(fmaxf(bfhi(hw.x), 1e-20f));
;                     v0[2] *= bflo(gw.y) * __builtin_amdgcn_rcpf(fmaxf(bflo(hw.y), 1e-20f)); v0[3] *= bfhi(gw.y) * __builtin_amdgcn_rcpf(fmaxf(bfhi(hw.y), 1e-20f));
;                     v1[0] *= bflo(gw.z) * __builtin_amdgcn_rcpf(fmaxf(bflo(hw.z), 1e-20f)); v1[1] *= bfhi(gw.z) * __builtin_amdgcn_rcpf(fmaxf(bfhi(hw.z), 1e-20f));
;                     v1[2] *= bflo(gw.w) * __builtin_amdgcn_rcpf(fmaxf(bflo(hw.w), 1e-20f)); v1[3] *= bfhi(gw.w) * __builtin_amdgcn_rcpf(fmaxf(bfhi(hw.w), 1e-20f));
;                     acc[ai][bj][m][0] = v0; acc[ai][bj][m][1] = v1;
	v_lshlrev_b32_e32 v246, 16, v226
	v_and_b32_e32 v247, 0xffff0000, v226
	v_max_f32_e32 v246, 0x1e3ce508, v246
	v_max_f32_e32 v247, 0x1e3ce508, v247
	v_rcp_f32_e32 v246, v246
	v_rcp_f32_e32 v247, v247
	v_lshlrev_b32_e32 v248, 16, v222
	v_and_b32_e32 v249, 0xffff0000, v222
	v_pk_mul_f32 v[248:249], v[246:247], v[248:249]
	v_pk_mul_f32 v[102:103], v[102:103], v[248:249]
	v_lshlrev_b32_e32 v250, 16, v227
	v_and_b32_e32 v251, 0xffff0000, v227
	v_max_f32_e32 v250, 0x1e3ce508, v250
	v_max_f32_e32 v251, 0x1e3ce508, v251
	v_rcp_f32_e32 v250, v250
	v_rcp_f32_e32 v251, v251
	v_lshlrev_b32_e32 v252, 16, v223
	v_and_b32_e32 v253, 0xffff0000, v223
	v_pk_mul_f32 v[252:253], v[250:251], v[252:253]
	v_pk_mul_f32 v[104:105], v[104:105], v[252:253]
	v_lshlrev_b32_e32 v246, 16, v228
	v_and_b32_e32 v247, 0xffff0000, v228
	v_max_f32_e32 v246, 0x1e3ce508, v246
	v_max_f32_e32 v247, 0x1e3ce508, v247
	v_rcp_f32_e32 v246, v246
	v_rcp_f32_e32 v247, v247
	v_lshlrev_b32_e32 v248, 16, v224
	v_and_b32_e32 v249, 0xffff0000, v224
	v_pk_mul_f32 v[248:249], v[246:247], v[248:249]
	v_pk_mul_f32 v[98:99], v[98:99], v[248:249]
	v_lshlrev_b32_e32 v250, 16, v229
	v_and_b32_e32 v251, 0xffff0000, v229
	v_max_f32_e32 v250, 0x1e3ce508, v250
	v_max_f32_e32 v251, 0x1e3ce508, v251
	v_rcp_f32_e32 v250, v250
	v_rcp_f32_e32 v251, v251
	v_lshlrev_b32_e32 v252, 16, v225
	v_and_b32_e32 v253, 0xffff0000, v225
	v_pk_mul_f32 v[252:253], v[250:251], v[252:253]
	v_pk_mul_f32 v[100:101], v[100:101], v[252:253]
	s_waitcnt vmcnt(6)
	v_lshlrev_b32_e32 v246, 16, v234
	v_and_b32_e32 v247, 0xffff0000, v234
	v_max_f32_e32 v246, 0x1e3ce508, v246
	v_max_f32_e32 v247, 0x1e3ce508, v247
	v_rcp_f32_e32 v246, v246
	v_rcp_f32_e32 v247, v247
	v_lshlrev_b32_e32 v248, 16, v230
	v_and_b32_e32 v249, 0xffff0000, v230
	v_pk_mul_f32 v[248:249], v[246:247], v[248:249]
	v_pk_mul_f32 v[94:95], v[94:95], v[248:249]
	v_lshlrev_b32_e32 v250, 16, v235
	v_and_b32_e32 v251, 0xffff0000, v235
	v_max_f32_e32 v250, 0x1e3ce508, v250
	v_max_f32_e32 v251, 0x1e3ce508, v251
	v_rcp_f32_e32 v250, v250
	v_rcp_f32_e32 v251, v251
	v_lshlrev_b32_e32 v252, 16, v231
	v_and_b32_e32 v253, 0xffff0000, v231
	v_pk_mul_f32 v[252:253], v[250:251], v[252:253]
	v_pk_mul_f32 v[96:97], v[96:97], v[252:253]
	v_lshlrev_b32_e32 v246, 16, v236
	v_and_b32_e32 v247, 0xffff0000, v236
	v_max_f32_e32 v246, 0x1e3ce508, v246
	v_max_f32_e32 v247, 0x1e3ce508, v247
	v_rcp_f32_e32 v246, v246
	v_rcp_f32_e32 v247, v247
	v_lshlrev_b32_e32 v248, 16, v232
	v_and_b32_e32 v249, 0xffff0000, v232
	v_pk_mul_f32 v[248:249], v[246:247], v[248:249]
	v_pk_mul_f32 v[90:91], v[90:91], v[248:249]
	v_lshlrev_b32_e32 v250, 16, v237
	v_and_b32_e32 v251, 0xffff0000, v237
	v_max_f32_e32 v250, 0x1e3ce508, v250
	v_max_f32_e32 v251, 0x1e3ce508, v251
	v_rcp_f32_e32 v250, v250
	v_rcp_f32_e32 v251, v251
	v_lshlrev_b32_e32 v252, 16, v233
	v_and_b32_e32 v253, 0xffff0000, v233
	v_pk_mul_f32 v[252:253], v[250:251], v[252:253]
	v_pk_mul_f32 v[92:93], v[92:93], v[252:253]
	s_waitcnt vmcnt(4)
	v_lshlrev_b32_e32 v246, 16, v130
	v_and_b32_e32 v247, 0xffff0000, v130
	v_max_f32_e32 v246, 0x1e3ce508, v246
	v_max_f32_e32 v247, 0x1e3ce508, v247
	v_rcp_f32_e32 v246, v246
	v_rcp_f32_e32 v247, v247
	v_lshlrev_b32_e32 v248, 16, v238
	v_and_b32_e32 v249, 0xffff0000, v238
	v_pk_mul_f32 v[248:249], v[246:247], v[248:249]
	v_pk_mul_f32 v[86:87], v[86:87], v[248:249]
	v_lshlrev_b32_e32 v250, 16, v131
	v_and_b32_e32 v251, 0xffff0000, v131
	v_max_f32_e32 v250, 0x1e3ce508, v250
	v_max_f32_e32 v251, 0x1e3ce508, v251
	v_rcp_f32_e32 v250, v250
	v_rcp_f32_e32 v251, v251
	v_lshlrev_b32_e32 v252, 16, v239
	v_and_b32_e32 v253, 0xffff0000, v239
	v_pk_mul_f32 v[252:253], v[250:251], v[252:253]
	v_pk_mul_f32 v[88:89], v[88:89], v[252:253]
	v_lshlrev_b32_e32 v246, 16, v132
	v_and_b32_e32 v247, 0xffff0000, v132
	v_max_f32_e32 v246, 0x1e3ce508, v246
	v_max_f32_e32 v247, 0x1e3ce508, v247
	v_rcp_f32_e32 v246, v246
	v_rcp_f32_e32 v247, v247
	v_lshlrev_b32_e32 v248, 16, v240
	v_and_b32_e32 v249, 0xffff0000, v240
	v_pk_mul_f32 v[248:249], v[246:247], v[248:249]
	v_pk_mul_f32 v[82:83], v[82:83], v[248:249]
	v_lshlrev_b32_e32 v250, 16, v133
	v_and_b32_e32 v251, 0xffff0000, v133
	v_max_f32_e32 v250, 0x1e3ce508, v250
	v_max_f32_e32 v251, 0x1e3ce508, v251
	v_rcp_f32_e32 v250, v250
	v_rcp_f32_e32 v251, v251
	v_lshlrev_b32_e32 v252, 16, v241
	v_and_b32_e32 v253, 0xffff0000, v241
	v_pk_mul_f32 v[252:253], v[250:251], v[252:253]
	v_pk_mul_f32 v[84:85], v[84:85], v[252:253]
	s_waitcnt vmcnt(2)
	v_lshlrev_b32_e32 v246, 16, v170
	v_and_b32_e32 v247, 0xffff0000, v170
	v_max_f32_e32 v246, 0x1e3ce508, v246
	v_max_f32_e32 v247, 0x1e3ce508, v247
	v_rcp_f32_e32 v246, v246
	v_rcp_f32_e32 v247, v247
	v_lshlrev_b32_e32 v248, 16, v134
	v_and_b32_e32 v249, 0xffff0000, v134
	v_pk_mul_f32 v[248:249], v[246:247], v[248:249]
	v_pk_mul_f32 v[78:79], v[78:79], v[248:249]
	v_lshlrev_b32_e32 v250, 16, v171
	v_and_b32_e32 v251, 0xffff0000, v171
	v_max_f32_e32 v250, 0x1e3ce508, v250
	v_max_f32_e32 v251, 0x1e3ce508, v251
	v_rcp_f32_e32 v250, v250
	v_rcp_f32_e32 v251, v251
	v_lshlrev_b32_e32 v252, 16, v135
	v_and_b32_e32 v253, 0xffff0000, v135
	v_pk_mul_f32 v[252:253], v[250:251], v[252:253]
	v_pk_mul_f32 v[80:81], v[80:81], v[252:253]
	v_lshlrev_b32_e32 v246, 16, v172
	v_and_b32_e32 v247, 0xffff0000, v172
	v_max_f32_e32 v246, 0x1e3ce508, v246
	v_max_f32_e32 v247, 0x1e3ce508, v247
	v_rcp_f32_e32 v246, v246
	v_rcp_f32_e32 v247, v247
	v_lshlrev_b32_e32 v248, 16, v136
	v_and_b32_e32 v249, 0xffff0000, v136
	v_pk_mul_f32 v[248:249], v[246:247], v[248:249]
	v_pk_mul_f32 v[74:75], v[74:75], v[248:249]
	v_lshlrev_b32_e32 v250, 16, v173
	v_and_b32_e32 v251, 0xffff0000, v173
	v_max_f32_e32 v250, 0x1e3ce508, v250
	v_max_f32_e32 v251, 0x1e3ce508, v251
	v_rcp_f32_e32 v250, v250
	v_rcp_f32_e32 v251, v251
	v_lshlrev_b32_e32 v252, 16, v137
	v_and_b32_e32 v253, 0xffff0000, v137
	v_pk_mul_f32 v[252:253], v[250:251], v[252:253]
	v_pk_mul_f32 v[76:77], v[76:77], v[252:253]
	s_waitcnt vmcnt(0)
; __device__ __forceinline__ float bflo(unsigned w) { return __uint_as_float(w << 16); }
; __device__ __forceinline__ float bfhi(unsigned w) { return __uint_as_float(w & 0xffff0000u); }
;     __device__ __forceinline__ void mid(f32x4 (&acc)[2][2][4][2], const pg8::Unit& u, int seg, int wr, int wc, int fr, int fq) const {
;     ...
;         for (int ai = 0; ai < 2; ++ai)
; #pragma unroll
;             for (int m = 0; m < 4; ++m) {
;                 const bf16_t* gp = gates + (size_t)(row0 + ai * 128 + m * 16) * 3072 + seg * 1024 + col0;
; #pragma unroll
;                 for (int bj = 0; bj < 2; ++bj) {
;                     const u32x4 gw = *(const u32x4*)(gp + bj * 128), hw = *(const u32x4*)(gp + 1024 + bj * 128);
;                     f32x4 v0 = acc[ai][bj][m][0], v1 = acc[ai][bj][m][1];
;                     v0[0] *= bflo(gw.x) * __builtin_amdgcn_rcpf(fmaxf(bflo(hw.x), 1e-20f)); v0[1] *= bfhi(gw.x) * __builtin_amdgcn_rcpf(fmaxf(bfhi(hw.x), 1e-20f));
;                     v0[2] *= bflo(gw.y) * __builtin_amdgcn_rcpf(fmaxf(bflo(hw.y), 1e-20f)); v0[3] *= bfhi(gw.y) * __builtin_amdgcn_rcpf(fmaxf(bfhi(hw.y), 1e-20f));
;                     v1[0] *= bflo(gw.z) * __builtin_amdgcn_rcpf(fmaxf(bflo(hw.z), 1e-20f)); v1[1] *= bfhi(gw.z) * __builtin_amdgcn_rcpf(fmaxf(bfhi(hw.z), 1e-20f));
;                     v1[2] *= bflo(gw.w) * __builtin_amdgcn_rcpf(fmaxf(bflo(hw.w), 1e-20f)); v1[3] *= bfhi(gw.w) * __builtin_amdgcn_rcpf(fmaxf(bfhi(hw.w), 1e-20f));
;                     acc[ai][bj][m][0] = v0; acc[ai][bj][m][1] = v1;
	v_lshlrev_b32_e32 v246, 16, v178
	v_and_b32_e32 v247, 0xffff0000, v178
	v_max_f32_e32 v246, 0x1e3ce508, v246
	v_max_f32_e32 v247, 0x1e3ce508, v247
	v_rcp_f32_e32 v246, v246
	v_rcp_f32_e32 v247, v247
	v_lshlrev_b32_e32 v248, 16, v174
	v_and_b32_e32 v249, 0xffff0000, v174
	v_pk_mul_f32 v[248:249], v[246:247], v[248:249]
	v_pk_mul_f32 v[70:71], v[70:71], v[248:249]
	v_lshlrev_b32_e32 v250, 16, v179
	v_and_b32_e32 v251, 0xffff0000, v179
	v_max_f32_e32 v250, 0x1e3ce508, v250
	v_max_f32_e32 v251, 0x1e3ce508, v251
	v_rcp_f32_e32 v250, v250
	v_rcp_f32_e32 v251, v251
	v_lshlrev_b32_e32 v252, 16, v175
	v_and_b32_e32 v253, 0xffff0000, v175
	v_pk_mul_f32 v[252:253], v[250:251], v[252:253]
	v_pk_mul_f32 v[72:73], v[72:73], v[252:253]
	v_lshlrev_b32_e32 v246, 16, v180
	v_and_b32_e32 v247, 0xffff0000, v180
	v_max_f32_e32 v246, 0x1e3ce508, v246
	v_max_f32_e32 v247, 0x1e3ce508, v247
	v_rcp_f32_e32 v246, v246
	v_rcp_f32_e32 v247, v247
	v_lshlrev_b32_e32 v248, 16, v176
	v_and_b32_e32 v249, 0xffff0000, v176
	v_pk_mul_f32 v[248:249], v[246:247], v[248:249]
	v_pk_mul_f32 v[66:67], v[66:67], v[248:249]
	v_lshlrev_b32_e32 v250, 16, v181
	v_and_b32_e32 v251, 0xffff0000, v181
	v_max_f32_e32 v250, 0x1e3ce508, v250
	v_max_f32_e32 v251, 0x1e3ce508, v251
	v_rcp_f32_e32 v250, v250
	v_rcp_f32_e32 v251, v251
	v_lshlrev_b32_e32 v252, 16, v177
	v_and_b32_e32 v253, 0xffff0000, v177
	v_pk_mul_f32 v[252:253], v[250:251], v[252:253]
	v_pk_mul_f32 v[68:69], v[68:69], v[252:253]
	v_add_u32_e32 v163, 0xc0000, v162
	global_load_dwordx4 v[198:201], v163, s[12:13]
	global_load_dwordx4 v[202:205], v163, s[12:13] offset:2048
	global_load_dwordx4 v[206:209], v163, s[12:13] offset:256
	global_load_dwordx4 v[210:213], v163, s[12:13] offset:2304
	v_add_u32_e32 v163, 0xd8000, v162
	global_load_dwordx4 v[214:217], v163, s[12:13]
	global_load_dwordx4 v[218:221], v163, s[12:13] offset:2048
	global_load_dwordx4 v[222:225], v163, s[12:13] offset:256
	global_load_dwordx4 v[226:229], v163, s[12:13] offset:2304
	v_add_u32_e32 v163, 0xf0000, v162
	global_load_dwordx4 v[230:233], v163, s[12:13]
	global_load_dwordx4 v[234:237], v163, s[12:13] offset:2048
	global_load_dwordx4 v[238:241], v163, s[12:13] offset:256
	global_load_dwordx4 v[130:133], v163, s[12:13] offset:2304
	v_add_u32_e32 v163, 0x108000, v162
	global_load_dwordx4 v[134:137], v163, s[12:13]
	global_load_dwordx4 v[170:173], v163, s[12:13] offset:2048
	global_load_dwordx4 v[174:177], v163, s[12:13] offset:256
	global_load_dwordx4 v[178:181], v163, s[12:13] offset:2304
	s_waitcnt vmcnt(14)
	v_lshlrev_b32_e32 v246, 16, v202
	v_and_b32_e32 v247, 0xffff0000, v202
	v_max_f32_e32 v246, 0x1e3ce508, v246
	v_max_f32_e32 v247, 0x1e3ce508, v247
	v_rcp_f32_e32 v246, v246
	v_rcp_f32_e32 v247, v247
	v_lshlrev_b32_e32 v248, 16, v198
	v_and_b32_e32 v249, 0xffff0000, v198
	v_pk_mul_f32 v[248:249], v[246:247], v[248:249]
	v_pk_mul_f32 v[62:63], v[62:63], v[248:249]
	v_lshlrev_b32_e32 v250, 16, v203
	v_and_b32_e32 v251, 0xffff0000, v203
	v_max_f32_e32 v250, 0x1e3ce508, v250
	v_max_f32_e32 v251, 0x1e3ce508, v251
	v_rcp_f32_e32 v250, v250
	v_rcp_f32_e32 v251, v251
	v_lshlrev_b32_e32 v252, 16, v199
	v_and_b32_e32 v253, 0xffff0000, v199
	v_pk_mul_f32 v[252:253], v[250:251], v[252:253]
	v_pk_mul_f32 v[64:65], v[64:65], v[252:253]
	v_lshlrev_b32_e32 v246, 16, v204
	v_and_b32_e32 v247, 0xffff0000, v204
	v_max_f32_e32 v246, 0x1e3ce508, v246
	v_max_f32_e32 v247, 0x1e3ce508, v247
	v_rcp_f32_e32 v246, v246
	v_rcp_f32_e32 v247, v247
	v_lshlrev_b32_e32 v248, 16, v200
	v_and_b32_e32 v249, 0xffff0000, v200
	v_pk_mul_f32 v[248:249], v[246:247], v[248:249]
	v_pk_mul_f32 v[58:59], v[58:59], v[248:249]
	v_lshlrev_b32_e32 v250, 16, v205
	v_and_b32_e32 v251, 0xffff0000, v205
	v_max_f32_e32 v250, 0x1e3ce508, v250
	v_max_f32_e32 v251, 0x1e3ce508, v251
	v_rcp_f32_e32 v250, v250
	v_rcp_f32_e32 v251, v251
	v_lshlrev_b32_e32 v252, 16, v201
	v_and_b32_e32 v253, 0xffff0000, v201
	v_pk_mul_f32 v[252:253], v[250:251], v[252:253]
	v_pk_mul_f32 v[60:61], v[60:61], v[252:253]
	s_waitcnt vmcnt(12)
	v_lshlrev_b32_e32 v246, 16, v210
	v_and_b32_e32 v247, 0xffff0000, v210
	v_max_f32_e32 v246, 0x1e3ce508, v246
	v_max_f32_e32 v247, 0x1e3ce508, v247
	v_rcp_f32_e32 v246, v246
	v_rcp_f32_e32 v247, v247
	v_lshlrev_b32_e32 v248, 16, v206
	v_and_b32_e32 v249, 0xffff0000, v206
	v_pk_mul_f32 v[248:249], v[246:247], v[248:249]
	v_pk_mul_f32 v[54:55], v[54:55], v[248:249]
	v_lshlrev_b32_e32 v250, 16, v211
	v_and_b32_e32 v251, 0xffff0000, v211
	v_max_f32_e32 v250, 0x1e3ce508, v250
	v_max_f32_e32 v251, 0x1e3ce508, v251
	v_rcp_f32_e32 v250, v250
	v_rcp_f32_e32 v251, v251
	v_lshlrev_b32_e32 v252, 16, v207
	v_and_b32_e32 v253, 0xffff0000, v207
	v_pk_mul_f32 v[252:253], v[250:251], v[252:253]
	v_pk_mul_f32 v[56:57], v[56:57], v[252:253]
	v_lshlrev_b32_e32 v246, 16, v212
	v_and_b32_e32 v247, 0xffff0000, v212
	v_max_f32_e32 v246, 0x1e3ce508, v246
	v_max_f32_e32 v247, 0x1e3ce508, v247
	v_rcp_f32_e32 v246, v246
	v_rcp_f32_e32 v247, v247
	v_lshlrev_b32_e32 v248, 16, v208
	v_and_b32_e32 v249, 0xffff0000, v208
	v_pk_mul_f32 v[248:249], v[246:247], v[248:249]
	v_pk_mul_f32 v[50:51], v[50:51], v[248:249]
	v_lshlrev_b32_e32 v250, 16, v213
	v_and_b32_e32 v251, 0xffff0000, v213
	v_max_f32_e32 v250, 0x1e3ce508, v250
	v_max_f32_e32 v251, 0x1e3ce508, v251
	v_rcp_f32_e32 v250, v250
	v_rcp_f32_e32 v251, v251
	v_lshlrev_b32_e32 v252, 16, v209
	v_and_b32_e32 v253, 0xffff0000, v209
	v_pk_mul_f32 v[252:253], v[250:251], v[252:253]
	v_pk_mul_f32 v[52:53], v[52:53], v[252:253]
	s_waitcnt vmcnt(10)
; __device__ __forceinline__ float bflo(unsigned w) { return __uint_as_float(w << 16); }
; __device__ __forceinline__ float bfhi(unsigned w) { return __uint_as_float(w & 0xffff0000u); }
;     __device__ __forceinline__ void mid(f32x4 (&acc)[2][2][4][2], const pg8::Unit& u, int seg, int wr, int wc, int fr, int fq) const {
;     ...
;                 const bf16_t* gp = gates + (size_t)(row0 + ai * 128 + m * 16) * 3072 + seg * 1024 + col0;
; #pragma unroll
;                 for (int bj = 0; bj < 2; ++bj) {
;                     const u32x4 gw = *(const u32x4*)(gp + bj * 128), hw = *(const u32x4*)(gp + 1024 + bj * 128);
;                     f32x4 v0 = acc[ai][bj][m][0], v1 = acc[ai][bj][m][1];
;                     v0[0] *= bflo(gw.x) * __builtin_amdgcn_rcpf(fmaxf(bflo(hw.x), 1e-20f)); v0[1] *= bfhi(gw.x) * __builtin_amdgcn_rcpf(fmaxf(bfhi(hw.x), 1e-20f));
;                     v0[2] *= bflo(gw.y) * __builtin_amdgcn_rcpf(fmaxf(bflo(hw.y), 1e-20f)); v0[3] *= bfhi(gw.y) * __builtin_amdgcn_rcpf(fmaxf(bfhi(hw.y), 1e-20f));
;                     v1[0] *= bflo(gw.z) * __builtin_amdgcn_rcpf(fmaxf(bflo(hw.z), 1e-20f)); v1[1] *= bfhi(gw.z) * __builtin_amdgcn_rcpf(fmaxf(bfhi(hw.z), 1e-20f));
;                     v1[2] *= bflo(gw.w) * __builtin_amdgcn_rcpf(fmaxf(bflo(hw.w), 1e-20f)); v1[3] *= bfhi(gw.w) * __builtin_amdgcn_rcpf(fmaxf(bfhi(hw.w), 1e-20f));
;                     acc[ai][bj][m][0] = v0; acc[ai][bj][m][1] = v1;
	v_lshlrev_b32_e32 v246, 16, v218
	v_and_b32_e32 v247, 0xffff0000, v218
	v_max_f32_e32 v246, 0x1e3ce508, v246
	v_max_f32_e32 v247, 0x1e3ce508, v247
	v_rcp_f32_e32 v246, v246
	v_rcp_f32_e32 v247, v247
	v_lshlrev_b32_e32 v248, 16, v214
	v_and_b32_e32 v249, 0xffff0000, v214
	v_pk_mul_f32 v[248:249], v[246:247], v[248:249]
	v_pk_mul_f32 v[46:47], v[46:47], v[248:249]
	v_lshlrev_b32_e32 v250, 16, v219
	v_and_b32_e32 v251, 0xffff0000, v219
	v_max_f32_e32 v250, 0x1e3ce508, v250
	v_max_f32_e32 v251, 0x1e3ce508, v251
	v_rcp_f32_e32 v250, v250
	v_rcp_f32_e32 v251, v251
	v_lshlrev_b32_e32 v252, 16, v215
	v_and_b32_e32 v253, 0xffff0000, v215
	v_pk_mul_f32 v[252:253], v[250:251], v[252:253]
	v_pk_mul_f32 v[48:49], v[48:49], v[252:253]
	v_lshlrev_b32_e32 v246, 16, v220
	v_and_b32_e32 v247, 0xffff0000, v220
	v_max_f32_e32 v246, 0x1e3ce508, v246
	v_max_f32_e32 v247, 0x1e3ce508, v247
	v_rcp_f32_e32 v246, v246
	v_rcp_f32_e32 v247, v247
	v_lshlrev_b32_e32 v248, 16, v216
	v_and_b32_e32 v249, 0xffff0000, v216
	v_pk_mul_f32 v[248:249], v[246:247], v[248:249]
	v_pk_mul_f32 v[42:43], v[42:43], v[248:249]
	v_lshlrev_b32_e32 v250, 16, v221
	v_and_b32_e32 v251, 0xffff0000, v221
	v_max_f32_e32 v250, 0x1e3ce508, v250
	v_max_f32_e32 v251, 0x1e3ce508, v251
	v_rcp_f32_e32 v250, v250
	v_rcp_f32_e32 v251, v251
	v_lshlrev_b32_e32 v252, 16, v217
	v_and_b32_e32 v253, 0xffff0000, v217
	v_pk_mul_f32 v[252:253], v[250:251], v[252:253]
	v_pk_mul_f32 v[44:45], v[44:45], v[252:253]
	s_waitcnt vmcnt(8)
	v_lshlrev_b32_e32 v246, 16, v226
	v_and_b32_e32 v247, 0xffff0000, v226
	v_max_f32_e32 v246, 0x1e3ce508, v246
	v_max_f32_e32 v247, 0x1e3ce508, v247
	v_rcp_f32_e32 v246, v246
	v_rcp_f32_e32 v247, v247
	v_lshlrev_b32_e32 v248, 16, v222
	v_and_b32_e32 v249, 0xffff0000, v222
	v_pk_mul_f32 v[248:249], v[246:247], v[248:249]
	v_pk_mul_f32 v[38:39], v[38:39], v[248:249]
	v_lshlrev_b32_e32 v250, 16, v227
	v_and_b32_e32 v251, 0xffff0000, v227
	v_max_f32_e32 v250, 0x1e3ce508, v250
	v_max_f32_e32 v251, 0x1e3ce508, v251
	v_rcp_f32_e32 v250, v250
	v_rcp_f32_e32 v251, v251
	v_lshlrev_b32_e32 v252, 16, v223
	v_and_b32_e32 v253, 0xffff0000, v223
	v_pk_mul_f32 v[252:253], v[250:251], v[252:253]
	v_pk_mul_f32 v[40:41], v[40:41], v[252:253]
	v_lshlrev_b32_e32 v246, 16, v228
	v_and_b32_e32 v247, 0xffff0000, v228
	v_max_f32_e32 v246, 0x1e3ce508, v246
	v_max_f32_e32 v247, 0x1e3ce508, v247
	v_rcp_f32_e32 v246, v246
	v_rcp_f32_e32 v247, v247
	v_lshlrev_b32_e32 v248, 16, v224
	v_and_b32_e32 v249, 0xffff0000, v224
	v_pk_mul_f32 v[248:249], v[246:247], v[248:249]
	v_pk_mul_f32 v[34:35], v[34:35], v[248:249]
	v_lshlrev_b32_e32 v250, 16, v229
	v_and_b32_e32 v251, 0xffff0000, v229
	v_max_f32_e32 v250, 0x1e3ce508, v250
	v_max_f32_e32 v251, 0x1e3ce508, v251
	v_rcp_f32_e32 v250, v250
	v_rcp_f32_e32 v251, v251
	v_lshlrev_b32_e32 v252, 16, v225
	v_and_b32_e32 v253, 0xffff0000, v225
	v_pk_mul_f32 v[252:253], v[250:251], v[252:253]
	v_pk_mul_f32 v[36:37], v[36:37], v[252:253]
	s_waitcnt vmcnt(6)
	v_lshlrev_b32_e32 v246, 16, v234
	v_and_b32_e32 v247, 0xffff0000, v234
	v_max_f32_e32 v246, 0x1e3ce508, v246
	v_max_f32_e32 v247, 0x1e3ce508, v247
	v_rcp_f32_e32 v246, v246
	v_rcp_f32_e32 v247, v247
	v_lshlrev_b32_e32 v248, 16, v230
	v_and_b32_e32 v249, 0xffff0000, v230
	v_pk_mul_f32 v[248:249], v[246:247], v[248:249]
	v_pk_mul_f32 v[30:31], v[30:31], v[248:249]
	v_lshlrev_b32_e32 v250, 16, v235
	v_and_b32_e32 v251, 0xffff0000, v235
	v_max_f32_e32 v250, 0x1e3ce508, v250
	v_max_f32_e32 v251, 0x1e3ce508, v251
	v_rcp_f32_e32 v250, v250
	v_rcp_f32_e32 v251, v251
	v_lshlrev_b32_e32 v252, 16, v231
	v_and_b32_e32 v253, 0xffff0000, v231
	v_pk_mul_f32 v[252:253], v[250:251], v[252:253]
	v_pk_mul_f32 v[32:33], v[32:33], v[252:253]
	v_lshlrev_b32_e32 v246, 16, v236
	v_and_b32_e32 v247, 0xffff0000, v236
	v_max_f32_e32 v246, 0x1e3ce508, v246
	v_max_f32_e32 v247, 0x1e3ce508, v247
	v_rcp_f32_e32 v246, v246
	v_rcp_f32_e32 v247, v247
	v_lshlrev_b32_e32 v248, 16, v232
	v_and_b32_e32 v249, 0xffff0000, v232
	v_pk_mul_f32 v[248:249], v[246:247], v[248:249]
	v_pk_mul_f32 v[26:27], v[26:27], v[248:249]
	v_lshlrev_b32_e32 v250, 16, v237
	v_and_b32_e32 v251, 0xffff0000, v237
	v_max_f32_e32 v250, 0x1e3ce508, v250
	v_max_f32_e32 v251, 0x1e3ce508, v251
	v_rcp_f32_e32 v250, v250
	v_rcp_f32_e32 v251, v251
	v_lshlrev_b32_e32 v252, 16, v233
	v_and_b32_e32 v253, 0xffff0000, v233
	v_pk_mul_f32 v[252:253], v[250:251], v[252:253]
	v_pk_mul_f32 v[28:29], v[28:29], v[252:253]
	s_waitcnt vmcnt(4)
; __device__ __forceinline__ float bflo(unsigned w) { return __uint_as_float(w << 16); }
; __device__ __forceinline__ float bfhi(unsigned w) { return __uint_as_float(w & 0xffff0000u); }
;     __device__ __forceinline__ void mid(f32x4 (&acc)[2][2][4][2], const pg8::Unit& u, int seg, int wr, int wc, int fr, int fq) const {
;     ...
;                 const bf16_t* gp = gates + (size_t)(row0 + ai * 128 + m * 16) * 3072 + seg * 1024 + col0;
; #pragma unroll
;                 for (int bj = 0; bj < 2; ++bj) {
;                     const u32x4 gw = *(const u32x4*)(gp + bj * 128), hw = *(const u32x4*)(gp + 1024 + bj * 128);
;                     f32x4 v0 = acc[ai][bj][m][0], v1 = acc[ai][bj][m][1];
;                     v0[0] *= bflo(gw.x) * __builtin_amdgcn_rcpf(fmaxf(bflo(hw.x), 1e-20f)); v0[1] *= bfhi(gw.x) * __builtin_amdgcn_rcpf(fmaxf(bfhi(hw.x), 1e-20f));
;                     v0[2] *= bflo(gw.y) * __builtin_amdgcn_rcpf(fmaxf(bflo(hw.y), 1e-20f)); v0[3] *= bfhi(gw.y) * __builtin_amdgcn_rcpf(fmaxf(bfhi(hw.y), 1e-20f));
;                     v1[0] *= bflo(gw.z) * __builtin_amdgcn_rcpf(fmaxf(bflo(hw.z), 1e-20f)); v1[1] *= bfhi(gw.z) * __builtin_amdgcn_rcpf(fmaxf(bfhi(hw.z), 1e-20f));
;                     v1[2] *= bflo(gw.w) * __builtin_amdgcn_rcpf(fmaxf(bflo(hw.w), 1e-20f)); v1[3] *= bfhi(gw.w) * __builtin_amdgcn_rcpf(fmaxf(bfhi(hw.w), 1e-20f));
;                     acc[ai][bj][m][0] = v0; acc[ai][bj][m][1] = v1;
;                 }
;                 if (m & 1) asm volatile("" ::: "memory");
;             }
	v_lshlrev_b32_e32 v246, 16, v130
	v_and_b32_e32 v247, 0xffff0000, v130
	v_max_f32_e32 v246, 0x1e3ce508, v246
	v_max_f32_e32 v247, 0x1e3ce508, v247
	v_rcp_f32_e32 v246, v246
	v_rcp_f32_e32 v247, v247
	v_lshlrev_b32_e32 v248, 16, v238
	v_and_b32_e32 v249, 0xffff0000, v238
	v_pk_mul_f32 v[248:249], v[246:247], v[248:249]
	v_pk_mul_f32 v[22:23], v[22:23], v[248:249]
	v_lshlrev_b32_e32 v250, 16, v131
	v_and_b32_e32 v251, 0xffff0000, v131
	v_max_f32_e32 v250, 0x1e3ce508, v250
	v_max_f32_e32 v251, 0x1e3ce508, v251
	v_rcp_f32_e32 v250, v250
	v_rcp_f32_e32 v251, v251
	v_lshlrev_b32_e32 v252, 16, v239
	v_and_b32_e32 v253, 0xffff0000, v239
	v_pk_mul_f32 v[252:253], v[250:251], v[252:253]
	v_pk_mul_f32 v[24:25], v[24:25], v[252:253]
	v_lshlrev_b32_e32 v246, 16, v132
	v_and_b32_e32 v247, 0xffff0000, v132
	v_max_f32_e32 v246, 0x1e3ce508, v246
	v_max_f32_e32 v247, 0x1e3ce508, v247
	v_rcp_f32_e32 v246, v246
	v_rcp_f32_e32 v247, v247
	v_lshlrev_b32_e32 v248, 16, v240
	v_and_b32_e32 v249, 0xffff0000, v240
	v_pk_mul_f32 v[248:249], v[246:247], v[248:249]
	v_pk_mul_f32 v[18:19], v[18:19], v[248:249]
	v_lshlrev_b32_e32 v250, 16, v133
	v_and_b32_e32 v251, 0xffff0000, v133
	v_max_f32_e32 v250, 0x1e3ce508, v250
	v_max_f32_e32 v251, 0x1e3ce508, v251
	v_rcp_f32_e32 v250, v250
	v_rcp_f32_e32 v251, v251
	v_lshlrev_b32_e32 v252, 16, v241
	v_and_b32_e32 v253, 0xffff0000, v241
	v_pk_mul_f32 v[252:253], v[250:251], v[252:253]
	v_pk_mul_f32 v[20:21], v[20:21], v[252:253]
	s_waitcnt vmcnt(2)
	v_lshlrev_b32_e32 v246, 16, v170
	v_and_b32_e32 v247, 0xffff0000, v170
	v_max_f32_e32 v246, 0x1e3ce508, v246
	v_max_f32_e32 v247, 0x1e3ce508, v247
	v_rcp_f32_e32 v246, v246
	v_rcp_f32_e32 v247, v247
	v_lshlrev_b32_e32 v248, 16, v134
	v_and_b32_e32 v249, 0xffff0000, v134
	v_pk_mul_f32 v[248:249], v[246:247], v[248:249]
	v_pk_mul_f32 v[14:15], v[14:15], v[248:249]
	v_lshlrev_b32_e32 v250, 16, v171
	v_and_b32_e32 v251, 0xffff0000, v171
	v_max_f32_e32 v250, 0x1e3ce508, v250
	v_max_f32_e32 v251, 0x1e3ce508, v251
	v_rcp_f32_e32 v250, v250
	v_rcp_f32_e32 v251, v251
	v_lshlrev_b32_e32 v252, 16, v135
	v_and_b32_e32 v253, 0xffff0000, v135
	v_pk_mul_f32 v[252:253], v[250:251], v[252:253]
	v_pk_mul_f32 v[16:17], v[16:17], v[252:253]
	v_lshlrev_b32_e32 v246, 16, v172
	v_and_b32_e32 v247, 0xffff0000, v172
	v_max_f32_e32 v246, 0x1e3ce508, v246
	v_max_f32_e32 v247, 0x1e3ce508, v247
	v_rcp_f32_e32 v246, v246
	v_rcp_f32_e32 v247, v247
	v_lshlrev_b32_e32 v248, 16, v136
	v_and_b32_e32 v249, 0xffff0000, v136
	v_pk_mul_f32 v[248:249], v[246:247], v[248:249]
	v_pk_mul_f32 v[10:11], v[10:11], v[248:249]
	v_lshlrev_b32_e32 v250, 16, v173
	v_and_b32_e32 v251, 0xffff0000, v173
	v_max_f32_e32 v250, 0x1e3ce508, v250
	v_max_f32_e32 v251, 0x1e3ce508, v251
	v_rcp_f32_e32 v250, v250
	v_rcp_f32_e32 v251, v251
	v_lshlrev_b32_e32 v252, 16, v137
	v_and_b32_e32 v253, 0xffff0000, v137
	v_pk_mul_f32 v[252:253], v[250:251], v[252:253]
	v_pk_mul_f32 v[12:13], v[12:13], v[252:253]
	s_waitcnt vmcnt(0)
	v_lshlrev_b32_e32 v246, 16, v178
	v_and_b32_e32 v247, 0xffff0000, v178
	v_max_f32_e32 v246, 0x1e3ce508, v246
	v_max_f32_e32 v247, 0x1e3ce508, v247
	v_rcp_f32_e32 v246, v246
	v_rcp_f32_e32 v247, v247
	v_lshlrev_b32_e32 v248, 16, v174
	v_and_b32_e32 v249, 0xffff0000, v174
	v_pk_mul_f32 v[248:249], v[246:247], v[248:249]
	v_pk_mul_f32 v[6:7], v[6:7], v[248:249]
	v_lshlrev_b32_e32 v250, 16, v179
	v_and_b32_e32 v251, 0xffff0000, v179
	v_max_f32_e32 v250, 0x1e3ce508, v250
	v_max_f32_e32 v251, 0x1e3ce508, v251
	v_rcp_f32_e32 v250, v250
	v_rcp_f32_e32 v251, v251
	v_lshlrev_b32_e32 v252, 16, v175
	v_and_b32_e32 v253, 0xffff0000, v175
	v_pk_mul_f32 v[252:253], v[250:251], v[252:253]
	v_pk_mul_f32 v[8:9], v[8:9], v[252:253]
	v_lshlrev_b32_e32 v246, 16, v180
	v_and_b32_e32 v247, 0xffff0000, v180
	v_max_f32_e32 v246, 0x1e3ce508, v246
	v_max_f32_e32 v247, 0x1e3ce508, v247
	v_rcp_f32_e32 v246, v246
	v_rcp_f32_e32 v247, v247
	v_lshlrev_b32_e32 v248, 16, v176
	v_and_b32_e32 v249, 0xffff0000, v176
	v_pk_mul_f32 v[248:249], v[246:247], v[248:249]
	v_pk_mul_f32 v[2:3], v[2:3], v[248:249]
	v_lshlrev_b32_e32 v250, 16, v181
	v_and_b32_e32 v251, 0xffff0000, v181
	v_max_f32_e32 v250, 0x1e3ce508, v250
	v_max_f32_e32 v251, 0x1e3ce508, v251
	v_rcp_f32_e32 v250, v250
	v_rcp_f32_e32 v251, v251
	v_lshlrev_b32_e32 v252, 16, v177
	v_and_b32_e32 v253, 0xffff0000, v177
	v_pk_mul_f32 v[252:253], v[250:251], v[252:253]
	v_pk_mul_f32 v[4:5], v[4:5], v[252:253]
	s_branch .LBB0_103
